# filt_main on the f32-operand matrix core (v_mfma_f32_32x32x2_f32, f32 in / f32 accumulate), rows staged in LDS, expf on VALU, 8-byte bf16 stores
# speedup vs baseline: 1.0784x; 1.0134x over previous
.Lfilt_fast:
	s_mov_b32 s99, 0x3fb8aa3b
	s_mov_b32 s4, s94
	s_mov_b32 s100, 0
	s_mov_b32 s101, 2
	v_and_b32_e32 v251, 31, v176
	v_bfe_u32 v232, v176, 5, 1
	v_mul_u32_u24_e32 v221, 272, v251
	v_lshl_add_u32 v221, v232, 2, v221
	v_lshlrev_b32_e32 v220, 4, v232
	v_add_u32_e32 v220, 17408, v220
.Lff_item:
	s_lshr_b32 s0, s4, 4
	s_and_b32 s1, s4, 15
	v_readlane_b32 s72, v252, 12
	v_readlane_b32 s73, v252, 13
	v_readlane_b32 s6, v252, 8
	v_readlane_b32 s7, v252, 9
	v_readlane_b32 s74, v252, 10
	v_readlane_b32 s75, v252, 11
	s_cmp_lt_u32 s0, 32
	s_movk_i32 s5, 0xff
	s_cmovk_i32 s5, 0x7ff
	s_cselect_b32 s93, 0, 32
	s_cselect_b32 s98, 0x10000, 0
	s_cselect_b32 s74, s74, s6
	s_cselect_b32 s75, s75, s7
	s_cselect_b32 s3, 13, 10
	s_add_u32 s72, s72, s98
	s_addc_u32 s73, s73, 0
	s_sub_i32 s0, s0, s93
	s_lshl_b32 s0, s0, 6
	s_lshr_b32 s96, s1, 2
	s_and_b32 s96, s96, 1
	s_add_i32 s2, s0, s96
	s_add_i32 s6, s5, 1
	s_add_i32 s93, s6, s0
	s_sub_i32 s98, s6, s0
	s_add_i32 s98, s98, -8
	s_cmp_lg_u32 s96, 0
	s_cselect_b32 s0, s93, s98
	s_cselect_b32 s7, 8, -8
	s_cselect_b32 s6, 0, 8
	s_lshl_b32 s0, s0, 1
	s_add_u32 s74, s74, s0
	s_addc_u32 s75, s75, 0
	s_barrier
	v_lshrrev_b32_e32 v251, 4, v176
	v_and_b32_e32 v98, 15, v176
	v_lshlrev_b32_e32 v98, 4, v98
	v_add_u32_e32 v99, 0, v251
	v_add_u32_e32 v100, s2, v99
	v_min_u32_e32 v100, s5, v100
	v_lshl_add_u32 v100, v100, 8, v98
	global_load_dwordx4 v[66:69], v100, s[72:73]
	v_add_u32_e32 v99, 16, v251
	v_add_u32_e32 v100, s2, v99
	v_min_u32_e32 v100, s5, v100
	v_lshl_add_u32 v100, v100, 8, v98
	global_load_dwordx4 v[70:73], v100, s[72:73]
	v_add_u32_e32 v99, 32, v251
	v_add_u32_e32 v100, s2, v99
	v_min_u32_e32 v100, s5, v100
	v_lshl_add_u32 v100, v100, 8, v98
	global_load_dwordx4 v[74:77], v100, s[72:73]
	v_add_u32_e32 v99, 48, v251
	v_add_u32_e32 v100, s2, v99
	v_min_u32_e32 v100, s5, v100
	v_lshl_add_u32 v100, v100, 8, v98
	global_load_dwordx4 v[78:81], v100, s[72:73]
	s_lshl_b32 s1, s1, 8
	v_and_b32_e32 v99, 0xc0, v176
	v_and_b32_e32 v100, 31, v176
	v_add3_u32 v99, v99, v100, s1
	v_bfe_u32 v101, v176, 5, 1
	v_lshl_add_u32 v64, v101, 12, v99
	v_lshlrev_b32_e32 v64, 2, v64
	v_mov_b32_e32 v232, 0xc0447cbd
	v_and_b32_e32 v100, 0x3ff, v99
	v_lshrrev_b32_e32 v218, 11, v99
	v_lshl_add_u32 v218, v218, 10, v100
	v_lshlrev_b32_e32 v218, s3, v218
	v_mad_i32_i24 v218, v101, s7, v218
	v_add_u32_e32 v218, s6, v218
	v_cvt_f32_u32_e32 v100, v100
	v_fmamk_f32 v216, v100, 0xbc44ade8, v232
	v_add_u32_e32 v99, 32, v99
	v_and_b32_e32 v100, 0x3ff, v99
	v_lshrrev_b32_e32 v219, 11, v99
	v_lshl_add_u32 v219, v219, 10, v100
	v_lshlrev_b32_e32 v219, s3, v219
	v_mad_i32_i24 v219, v101, s7, v219
	v_add_u32_e32 v219, s6, v219
	v_cvt_f32_u32_e32 v100, v100
	v_fmamk_f32 v217, v100, 0xbc44ade8, v232
	s_mov_b32 s6, s78
	s_mov_b32 s7, s79
	global_load_dword v0, v64, s[6:7]
	global_load_dword v1, v64, s[6:7] offset:128
	s_add_u32 s6, s6, 0x8000
	s_addc_u32 s7, s7, 0
	global_load_dword v2, v64, s[6:7]
	global_load_dword v3, v64, s[6:7] offset:128
	s_add_u32 s6, s6, 0x8000
	s_addc_u32 s7, s7, 0
	global_load_dword v4, v64, s[6:7]
	global_load_dword v5, v64, s[6:7] offset:128
	s_add_u32 s6, s6, 0x8000
	s_addc_u32 s7, s7, 0
	global_load_dword v6, v64, s[6:7]
	global_load_dword v7, v64, s[6:7] offset:128
	s_add_u32 s6, s6, 0x8000
	s_addc_u32 s7, s7, 0
	global_load_dword v8, v64, s[6:7]
	global_load_dword v9, v64, s[6:7] offset:128
	s_add_u32 s6, s6, 0x8000
	s_addc_u32 s7, s7, 0
	global_load_dword v10, v64, s[6:7]
	global_load_dword v11, v64, s[6:7] offset:128
	s_add_u32 s6, s6, 0x8000
	s_addc_u32 s7, s7, 0
	global_load_dword v12, v64, s[6:7]
	global_load_dword v13, v64, s[6:7] offset:128
	s_add_u32 s6, s6, 0x8000
	s_addc_u32 s7, s7, 0
	global_load_dword v14, v64, s[6:7]
	global_load_dword v15, v64, s[6:7] offset:128
	s_add_u32 s6, s6, 0x8000
	s_addc_u32 s7, s7, 0
	global_load_dword v16, v64, s[6:7]
	global_load_dword v17, v64, s[6:7] offset:128
	s_add_u32 s6, s6, 0x8000
	s_addc_u32 s7, s7, 0
	global_load_dword v18, v64, s[6:7]
	global_load_dword v19, v64, s[6:7] offset:128
	s_add_u32 s6, s6, 0x8000
	s_addc_u32 s7, s7, 0
	global_load_dword v20, v64, s[6:7]
	global_load_dword v21, v64, s[6:7] offset:128
	s_add_u32 s6, s6, 0x8000
	s_addc_u32 s7, s7, 0
	global_load_dword v22, v64, s[6:7]
	global_load_dword v23, v64, s[6:7] offset:128
	s_add_u32 s6, s6, 0x8000
	s_addc_u32 s7, s7, 0
	global_load_dword v24, v64, s[6:7]
	global_load_dword v25, v64, s[6:7] offset:128
	s_add_u32 s6, s6, 0x8000
	s_addc_u32 s7, s7, 0
	global_load_dword v26, v64, s[6:7]
	global_load_dword v27, v64, s[6:7] offset:128
	s_add_u32 s6, s6, 0x8000
	s_addc_u32 s7, s7, 0
	global_load_dword v28, v64, s[6:7]
	global_load_dword v29, v64, s[6:7] offset:128
	s_add_u32 s6, s6, 0x8000
	s_addc_u32 s7, s7, 0
	global_load_dword v30, v64, s[6:7]
	global_load_dword v31, v64, s[6:7] offset:128
	s_add_u32 s6, s6, 0x8000
	s_addc_u32 s7, s7, 0
	global_load_dword v32, v64, s[6:7]
	global_load_dword v33, v64, s[6:7] offset:128
	s_add_u32 s6, s6, 0x8000
	s_addc_u32 s7, s7, 0
	global_load_dword v34, v64, s[6:7]
	global_load_dword v35, v64, s[6:7] offset:128
	s_add_u32 s6, s6, 0x8000
	s_addc_u32 s7, s7, 0
	global_load_dword v36, v64, s[6:7]
	global_load_dword v37, v64, s[6:7] offset:128
	s_add_u32 s6, s6, 0x8000
	s_addc_u32 s7, s7, 0
	global_load_dword v38, v64, s[6:7]
	global_load_dword v39, v64, s[6:7] offset:128
	s_add_u32 s6, s6, 0x8000
	s_addc_u32 s7, s7, 0
	global_load_dword v40, v64, s[6:7]
	global_load_dword v41, v64, s[6:7] offset:128
	s_add_u32 s6, s6, 0x8000
	s_addc_u32 s7, s7, 0
	global_load_dword v42, v64, s[6:7]
	global_load_dword v43, v64, s[6:7] offset:128
	s_add_u32 s6, s6, 0x8000
	s_addc_u32 s7, s7, 0
	global_load_dword v44, v64, s[6:7]
	global_load_dword v45, v64, s[6:7] offset:128
	s_add_u32 s6, s6, 0x8000
	s_addc_u32 s7, s7, 0
	global_load_dword v46, v64, s[6:7]
	global_load_dword v47, v64, s[6:7] offset:128
	s_add_u32 s6, s6, 0x8000
	s_addc_u32 s7, s7, 0
	global_load_dword v48, v64, s[6:7]
	global_load_dword v49, v64, s[6:7] offset:128
	s_add_u32 s6, s6, 0x8000
	s_addc_u32 s7, s7, 0
	global_load_dword v50, v64, s[6:7]
	global_load_dword v51, v64, s[6:7] offset:128
	s_add_u32 s6, s6, 0x8000
	s_addc_u32 s7, s7, 0
	global_load_dword v52, v64, s[6:7]
	global_load_dword v53, v64, s[6:7] offset:128
	s_add_u32 s6, s6, 0x8000
	s_addc_u32 s7, s7, 0
	global_load_dword v54, v64, s[6:7]
	global_load_dword v55, v64, s[6:7] offset:128
	s_add_u32 s6, s6, 0x8000
	s_addc_u32 s7, s7, 0
	v_cvt_f32_u32_e32 v82, s5
	v_and_b32_e32 v87, 63, v176
	v_add_u32_e32 v88, s2, v87
	v_cvt_f32_i32_e32 v83, v88
	v_div_scale_f32 v84, s[0:1], v82, v82, -v83
	v_rcp_f32_e32 v85, v84
	s_nop 0
	v_fma_f32 v86, -v84, v85, 1.0
	v_fmac_f32_e32 v85, v86, v85
	v_div_scale_f32 v86, vcc, -v83, v82, -v83
	v_mul_f32_e32 v88, v86, v85
	v_fma_f32 v89, -v84, v88, v86
	v_fmac_f32_e32 v88, v89, v85
	v_fma_f32 v84, -v84, v88, v86
	v_div_fmas_f32 v84, v84, v85, v88
	v_div_fixup_f32 v83, v84, v82, -v83
	v_lshlrev_b32_e32 v87, 2, v87
	ds_write_b32 v87, v83 offset:17408
	v_mul_u32_u24_e32 v99, 272, v251
	v_add_u32_e32 v99, v99, v98
	s_waitcnt vmcnt(56)
	ds_write_b128 v99, v[66:69] offset:0
	ds_write_b128 v99, v[70:73] offset:4352
	ds_write_b128 v99, v[74:77] offset:8704
	ds_write_b128 v99, v[78:81] offset:13056
	global_load_dword v56, v64, s[6:7]
	global_load_dword v57, v64, s[6:7] offset:128
	s_add_u32 s6, s6, 0x8000
	s_addc_u32 s7, s7, 0
	global_load_dword v58, v64, s[6:7]
	global_load_dword v59, v64, s[6:7] offset:128
	s_add_u32 s6, s6, 0x8000
	s_addc_u32 s7, s7, 0
	global_load_dword v60, v64, s[6:7]
	global_load_dword v61, v64, s[6:7] offset:128
	s_add_u32 s6, s6, 0x8000
	s_addc_u32 s7, s7, 0
	global_load_dword v62, v64, s[6:7]
	global_load_dword v63, v64, s[6:7] offset:128
	s_waitcnt lgkmcnt(0)
	s_barrier
	s_mov_b32 s3, s100
.Lff_pt:
	s_mul_i32 s0, s3, 8704
	s_lshl_b32 s1, s3, 7
	v_add_u32_e32 v249, s0, v221
	v_add_u32_e32 v250, s1, v220
	s_lshl_b32 s0, s3, 5
	s_add_i32 s0, s0, s2
	s_add_i32 s0, s0, 31
	s_cmp_gt_u32 s0, s5
	s_cselect_b32 s0, 0, -1
	v_mov_b32_e32 v251, s0
	v_bfe_u32 v232, v176, 5, 1
	v_cmp_eq_u32_e32 vcc, 1, v232
	v_mov_b32_e32 v232, -1
	s_nop 1
	v_cndmask_b32_e32 v232, v232, v251, vcc
	ds_read_b32 v98, v249 offset:0
	ds_read_b32 v99, v249 offset:8
	ds_read_b32 v100, v249 offset:16
	ds_read_b32 v101, v249 offset:24
	ds_read_b32 v102, v249 offset:32
	ds_read_b32 v103, v249 offset:40
	ds_read_b32 v104, v249 offset:48
	ds_read_b32 v105, v249 offset:56
	ds_read_b32 v106, v249 offset:64
	ds_read_b32 v107, v249 offset:72
	ds_read_b32 v108, v249 offset:80
	ds_read_b32 v109, v249 offset:88
	s_waitcnt vmcnt(0)
	s_waitcnt lgkmcnt(8)
	v_mfma_f32_32x32x2_f32 v[66:81], v98, v0, 0
	v_mfma_f32_32x32x2_f32 v[82:97], v98, v1, 0
	v_mfma_f32_32x32x2_f32 v[66:81], v99, v2, v[66:81]
	v_mfma_f32_32x32x2_f32 v[82:97], v99, v3, v[82:97]
	ds_read_b32 v110, v249 offset:96
	ds_read_b32 v111, v249 offset:104
	ds_read_b32 v112, v249 offset:112
	ds_read_b32 v113, v249 offset:120
	v_mfma_f32_32x32x2_f32 v[66:81], v100, v4, v[66:81]
	v_mfma_f32_32x32x2_f32 v[82:97], v100, v5, v[82:97]
	v_mfma_f32_32x32x2_f32 v[66:81], v101, v6, v[66:81]
	v_mfma_f32_32x32x2_f32 v[82:97], v101, v7, v[82:97]
	s_waitcnt lgkmcnt(8)
	v_mfma_f32_32x32x2_f32 v[66:81], v102, v8, v[66:81]
	v_mfma_f32_32x32x2_f32 v[82:97], v102, v9, v[82:97]
	v_mfma_f32_32x32x2_f32 v[66:81], v103, v10, v[66:81]
	v_mfma_f32_32x32x2_f32 v[82:97], v103, v11, v[82:97]
	ds_read_b32 v200, v249 offset:128
	ds_read_b32 v201, v249 offset:136
	ds_read_b32 v202, v249 offset:144
	ds_read_b32 v203, v249 offset:152
	v_mfma_f32_32x32x2_f32 v[66:81], v104, v12, v[66:81]
	v_mfma_f32_32x32x2_f32 v[82:97], v104, v13, v[82:97]
	v_mfma_f32_32x32x2_f32 v[66:81], v105, v14, v[66:81]
	v_mfma_f32_32x32x2_f32 v[82:97], v105, v15, v[82:97]
	s_waitcnt lgkmcnt(8)
	v_mfma_f32_32x32x2_f32 v[66:81], v106, v16, v[66:81]
	v_mfma_f32_32x32x2_f32 v[82:97], v106, v17, v[82:97]
	v_mfma_f32_32x32x2_f32 v[66:81], v107, v18, v[66:81]
	v_mfma_f32_32x32x2_f32 v[82:97], v107, v19, v[82:97]
	ds_read_b32 v204, v249 offset:160
	ds_read_b32 v205, v249 offset:168
	ds_read_b32 v206, v249 offset:176
	ds_read_b32 v207, v249 offset:184
	v_mfma_f32_32x32x2_f32 v[66:81], v108, v20, v[66:81]
	v_mfma_f32_32x32x2_f32 v[82:97], v108, v21, v[82:97]
	v_mfma_f32_32x32x2_f32 v[66:81], v109, v22, v[66:81]
	v_mfma_f32_32x32x2_f32 v[82:97], v109, v23, v[82:97]
	s_waitcnt lgkmcnt(8)
	v_mfma_f32_32x32x2_f32 v[66:81], v110, v24, v[66:81]
	v_mfma_f32_32x32x2_f32 v[82:97], v110, v25, v[82:97]
	v_mfma_f32_32x32x2_f32 v[66:81], v111, v26, v[66:81]
	v_mfma_f32_32x32x2_f32 v[82:97], v111, v27, v[82:97]
	ds_read_b32 v208, v249 offset:192
	ds_read_b32 v209, v249 offset:200
	ds_read_b32 v210, v249 offset:208
	ds_read_b32 v211, v249 offset:216
	v_mfma_f32_32x32x2_f32 v[66:81], v112, v28, v[66:81]
	v_mfma_f32_32x32x2_f32 v[82:97], v112, v29, v[82:97]
	v_mfma_f32_32x32x2_f32 v[66:81], v113, v30, v[66:81]
	v_mfma_f32_32x32x2_f32 v[82:97], v113, v31, v[82:97]
	s_waitcnt lgkmcnt(8)
	v_mfma_f32_32x32x2_f32 v[66:81], v200, v32, v[66:81]
	v_mfma_f32_32x32x2_f32 v[82:97], v200, v33, v[82:97]
	v_mfma_f32_32x32x2_f32 v[66:81], v201, v34, v[66:81]
	v_mfma_f32_32x32x2_f32 v[82:97], v201, v35, v[82:97]
	ds_read_b32 v212, v249 offset:224
	ds_read_b32 v213, v249 offset:232
	ds_read_b32 v214, v249 offset:240
	ds_read_b32 v215, v249 offset:248
	v_mfma_f32_32x32x2_f32 v[66:81], v202, v36, v[66:81]
	v_mfma_f32_32x32x2_f32 v[82:97], v202, v37, v[82:97]
	v_mfma_f32_32x32x2_f32 v[66:81], v203, v38, v[66:81]
	v_mfma_f32_32x32x2_f32 v[82:97], v203, v39, v[82:97]
	s_waitcnt lgkmcnt(8)
	v_mfma_f32_32x32x2_f32 v[66:81], v204, v40, v[66:81]
	v_mfma_f32_32x32x2_f32 v[82:97], v204, v41, v[82:97]
	v_mfma_f32_32x32x2_f32 v[66:81], v205, v42, v[66:81]
	v_mfma_f32_32x32x2_f32 v[82:97], v205, v43, v[82:97]
	ds_read_b32 v233, v250 offset:0
	ds_read_b32 v234, v250 offset:4
	ds_read_b32 v235, v250 offset:8
	ds_read_b32 v236, v250 offset:12
	v_mfma_f32_32x32x2_f32 v[66:81], v206, v44, v[66:81]
	v_mfma_f32_32x32x2_f32 v[82:97], v206, v45, v[82:97]
	v_mfma_f32_32x32x2_f32 v[66:81], v207, v46, v[66:81]
	v_mfma_f32_32x32x2_f32 v[82:97], v207, v47, v[82:97]
	s_waitcnt lgkmcnt(8)
	v_mfma_f32_32x32x2_f32 v[66:81], v208, v48, v[66:81]
	v_mfma_f32_32x32x2_f32 v[82:97], v208, v49, v[82:97]
	v_mfma_f32_32x32x2_f32 v[66:81], v209, v50, v[66:81]
	v_mfma_f32_32x32x2_f32 v[82:97], v209, v51, v[82:97]
	ds_read_b32 v237, v250 offset:32
	ds_read_b32 v238, v250 offset:36
	ds_read_b32 v239, v250 offset:40
	ds_read_b32 v240, v250 offset:44
	v_mfma_f32_32x32x2_f32 v[66:81], v210, v52, v[66:81]
	v_mfma_f32_32x32x2_f32 v[82:97], v210, v53, v[82:97]
	v_mfma_f32_32x32x2_f32 v[66:81], v211, v54, v[66:81]
	v_mfma_f32_32x32x2_f32 v[82:97], v211, v55, v[82:97]
	s_waitcnt lgkmcnt(8)
	v_mfma_f32_32x32x2_f32 v[66:81], v212, v56, v[66:81]
	v_mfma_f32_32x32x2_f32 v[82:97], v212, v57, v[82:97]
	v_mfma_f32_32x32x2_f32 v[66:81], v213, v58, v[66:81]
	v_mfma_f32_32x32x2_f32 v[82:97], v213, v59, v[82:97]
	ds_read_b32 v241, v250 offset:64
	ds_read_b32 v242, v250 offset:68
	ds_read_b32 v243, v250 offset:72
	ds_read_b32 v244, v250 offset:76
	v_mfma_f32_32x32x2_f32 v[66:81], v214, v60, v[66:81]
	v_mfma_f32_32x32x2_f32 v[82:97], v214, v61, v[82:97]
	v_mfma_f32_32x32x2_f32 v[66:81], v215, v62, v[66:81]
	v_mfma_f32_32x32x2_f32 v[82:97], v215, v63, v[82:97]
	ds_read_b32 v245, v250 offset:96
	ds_read_b32 v246, v250 offset:100
	ds_read_b32 v247, v250 offset:104
	ds_read_b32 v248, v250 offset:108
	s_waitcnt lgkmcnt(0)
	s_nop 15
	s_nop 3
	v_mul_f32_e64 v98, |v216|, v233
	v_mul_f32_e32 v99, 0x3fb8aa3b, v98
	v_fma_f32 v100, v98, s99, -v99
	v_rndne_f32_e32 v101, v99
	v_fmac_f32_e32 v100, 0x32a5705f, v98
	v_sub_f32_e32 v99, v99, v101
	v_add_f32_e32 v99, v99, v100
	v_exp_f32_e32 v99, v99
	v_cvt_i32_f32_e32 v100, v101
	v_cmp_ngt_f32_e32 vcc, 0xc2ce8ed0, v98
	v_ldexp_f32 v99, v99, v100
	s_nop 0
	v_cndmask_b32_e32 v99, 0, v99, vcc
	v_cmp_nlt_f32_e32 vcc, 0x42b17218, v98
	s_nop 1
	v_cndmask_b32_e32 v99, v192, v99, vcc
	v_mul_f32_e32 v66, v99, v66
	v_mul_f32_e64 v98, |v216|, v234
	v_mul_f32_e32 v99, 0x3fb8aa3b, v98
	v_fma_f32 v100, v98, s99, -v99
	v_rndne_f32_e32 v101, v99
	v_fmac_f32_e32 v100, 0x32a5705f, v98
	v_sub_f32_e32 v99, v99, v101
	v_add_f32_e32 v99, v99, v100
	v_exp_f32_e32 v99, v99
	v_cvt_i32_f32_e32 v100, v101
	v_cmp_ngt_f32_e32 vcc, 0xc2ce8ed0, v98
	v_ldexp_f32 v99, v99, v100
	s_nop 0
	v_cndmask_b32_e32 v99, 0, v99, vcc
	v_cmp_nlt_f32_e32 vcc, 0x42b17218, v98
	s_nop 1
	v_cndmask_b32_e32 v99, v192, v99, vcc
	v_mul_f32_e32 v67, v99, v67
	v_mul_f32_e64 v98, |v216|, v235
	v_mul_f32_e32 v99, 0x3fb8aa3b, v98
	v_fma_f32 v100, v98, s99, -v99
	v_rndne_f32_e32 v101, v99
	v_fmac_f32_e32 v100, 0x32a5705f, v98
	v_sub_f32_e32 v99, v99, v101
	v_add_f32_e32 v99, v99, v100
	v_exp_f32_e32 v99, v99
	v_cvt_i32_f32_e32 v100, v101
	v_cmp_ngt_f32_e32 vcc, 0xc2ce8ed0, v98
	v_ldexp_f32 v99, v99, v100
	s_nop 0
	v_cndmask_b32_e32 v99, 0, v99, vcc
	v_cmp_nlt_f32_e32 vcc, 0x42b17218, v98
	s_nop 1
	v_cndmask_b32_e32 v99, v192, v99, vcc
	v_mul_f32_e32 v68, v99, v68
	v_mul_f32_e64 v98, |v216|, v236
	v_mul_f32_e32 v99, 0x3fb8aa3b, v98
	v_fma_f32 v100, v98, s99, -v99
	v_rndne_f32_e32 v101, v99
	v_fmac_f32_e32 v100, 0x32a5705f, v98
	v_sub_f32_e32 v99, v99, v101
	v_add_f32_e32 v99, v99, v100
	v_exp_f32_e32 v99, v99
	v_cvt_i32_f32_e32 v100, v101
	v_cmp_ngt_f32_e32 vcc, 0xc2ce8ed0, v98
	v_ldexp_f32 v99, v99, v100
	s_nop 0
	v_cndmask_b32_e32 v99, 0, v99, vcc
	v_cmp_nlt_f32_e32 vcc, 0x42b17218, v98
	s_nop 1
	v_cndmask_b32_e32 v99, v192, v99, vcc
	v_mul_f32_e32 v69, v99, v69
	v_mul_f32_e64 v98, |v216|, v237
	v_mul_f32_e32 v99, 0x3fb8aa3b, v98
	v_fma_f32 v100, v98, s99, -v99
	v_rndne_f32_e32 v101, v99
	v_fmac_f32_e32 v100, 0x32a5705f, v98
	v_sub_f32_e32 v99, v99, v101
	v_add_f32_e32 v99, v99, v100
	v_exp_f32_e32 v99, v99
	v_cvt_i32_f32_e32 v100, v101
	v_cmp_ngt_f32_e32 vcc, 0xc2ce8ed0, v98
	v_ldexp_f32 v99, v99, v100
	s_nop 0
	v_cndmask_b32_e32 v99, 0, v99, vcc
	v_cmp_nlt_f32_e32 vcc, 0x42b17218, v98
	s_nop 1
	v_cndmask_b32_e32 v99, v192, v99, vcc
	v_mul_f32_e32 v70, v99, v70
	v_mul_f32_e64 v98, |v216|, v238
	v_mul_f32_e32 v99, 0x3fb8aa3b, v98
	v_fma_f32 v100, v98, s99, -v99
	v_rndne_f32_e32 v101, v99
	v_fmac_f32_e32 v100, 0x32a5705f, v98
	v_sub_f32_e32 v99, v99, v101
	v_add_f32_e32 v99, v99, v100
	v_exp_f32_e32 v99, v99
	v_cvt_i32_f32_e32 v100, v101
	v_cmp_ngt_f32_e32 vcc, 0xc2ce8ed0, v98
	v_ldexp_f32 v99, v99, v100
	s_nop 0
	v_cndmask_b32_e32 v99, 0, v99, vcc
	v_cmp_nlt_f32_e32 vcc, 0x42b17218, v98
	s_nop 1
	v_cndmask_b32_e32 v99, v192, v99, vcc
	v_mul_f32_e32 v71, v99, v71
	v_mul_f32_e64 v98, |v216|, v239
	v_mul_f32_e32 v99, 0x3fb8aa3b, v98
	v_fma_f32 v100, v98, s99, -v99
	v_rndne_f32_e32 v101, v99
	v_fmac_f32_e32 v100, 0x32a5705f, v98
	v_sub_f32_e32 v99, v99, v101
	v_add_f32_e32 v99, v99, v100
	v_exp_f32_e32 v99, v99
	v_cvt_i32_f32_e32 v100, v101
	v_cmp_ngt_f32_e32 vcc, 0xc2ce8ed0, v98
	v_ldexp_f32 v99, v99, v100
	s_nop 0
	v_cndmask_b32_e32 v99, 0, v99, vcc
	v_cmp_nlt_f32_e32 vcc, 0x42b17218, v98
	s_nop 1
	v_cndmask_b32_e32 v99, v192, v99, vcc
	v_mul_f32_e32 v72, v99, v72
	v_mul_f32_e64 v98, |v216|, v240
	v_mul_f32_e32 v99, 0x3fb8aa3b, v98
	v_fma_f32 v100, v98, s99, -v99
	v_rndne_f32_e32 v101, v99
	v_fmac_f32_e32 v100, 0x32a5705f, v98
	v_sub_f32_e32 v99, v99, v101
	v_add_f32_e32 v99, v99, v100
	v_exp_f32_e32 v99, v99
	v_cvt_i32_f32_e32 v100, v101
	v_cmp_ngt_f32_e32 vcc, 0xc2ce8ed0, v98
	v_ldexp_f32 v99, v99, v100
	s_nop 0
	v_cndmask_b32_e32 v99, 0, v99, vcc
	v_cmp_nlt_f32_e32 vcc, 0x42b17218, v98
	s_nop 1
	v_cndmask_b32_e32 v99, v192, v99, vcc
	v_mul_f32_e32 v73, v99, v73
	v_mul_f32_e64 v98, |v216|, v241
	v_mul_f32_e32 v99, 0x3fb8aa3b, v98
	v_fma_f32 v100, v98, s99, -v99
	v_rndne_f32_e32 v101, v99
	v_fmac_f32_e32 v100, 0x32a5705f, v98
	v_sub_f32_e32 v99, v99, v101
	v_add_f32_e32 v99, v99, v100
	v_exp_f32_e32 v99, v99
	v_cvt_i32_f32_e32 v100, v101
	v_cmp_ngt_f32_e32 vcc, 0xc2ce8ed0, v98
	v_ldexp_f32 v99, v99, v100
	s_nop 0
	v_cndmask_b32_e32 v99, 0, v99, vcc
	v_cmp_nlt_f32_e32 vcc, 0x42b17218, v98
	s_nop 1
	v_cndmask_b32_e32 v99, v192, v99, vcc
	v_mul_f32_e32 v74, v99, v74
	v_mul_f32_e64 v98, |v216|, v242
	v_mul_f32_e32 v99, 0x3fb8aa3b, v98
	v_fma_f32 v100, v98, s99, -v99
	v_rndne_f32_e32 v101, v99
	v_fmac_f32_e32 v100, 0x32a5705f, v98
	v_sub_f32_e32 v99, v99, v101
	v_add_f32_e32 v99, v99, v100
	v_exp_f32_e32 v99, v99
	v_cvt_i32_f32_e32 v100, v101
	v_cmp_ngt_f32_e32 vcc, 0xc2ce8ed0, v98
	v_ldexp_f32 v99, v99, v100
	s_nop 0
	v_cndmask_b32_e32 v99, 0, v99, vcc
	v_cmp_nlt_f32_e32 vcc, 0x42b17218, v98
	s_nop 1
	v_cndmask_b32_e32 v99, v192, v99, vcc
	v_mul_f32_e32 v75, v99, v75
	v_mul_f32_e64 v98, |v216|, v243
	v_mul_f32_e32 v99, 0x3fb8aa3b, v98
	v_fma_f32 v100, v98, s99, -v99
	v_rndne_f32_e32 v101, v99
	v_fmac_f32_e32 v100, 0x32a5705f, v98
	v_sub_f32_e32 v99, v99, v101
	v_add_f32_e32 v99, v99, v100
	v_exp_f32_e32 v99, v99
	v_cvt_i32_f32_e32 v100, v101
	v_cmp_ngt_f32_e32 vcc, 0xc2ce8ed0, v98
	v_ldexp_f32 v99, v99, v100
	s_nop 0
	v_cndmask_b32_e32 v99, 0, v99, vcc
	v_cmp_nlt_f32_e32 vcc, 0x42b17218, v98
	s_nop 1
	v_cndmask_b32_e32 v99, v192, v99, vcc
	v_mul_f32_e32 v76, v99, v76
	v_mul_f32_e64 v98, |v216|, v244
	v_mul_f32_e32 v99, 0x3fb8aa3b, v98
	v_fma_f32 v100, v98, s99, -v99
	v_rndne_f32_e32 v101, v99
	v_fmac_f32_e32 v100, 0x32a5705f, v98
	v_sub_f32_e32 v99, v99, v101
	v_add_f32_e32 v99, v99, v100
	v_exp_f32_e32 v99, v99
	v_cvt_i32_f32_e32 v100, v101
	v_cmp_ngt_f32_e32 vcc, 0xc2ce8ed0, v98
	v_ldexp_f32 v99, v99, v100
	s_nop 0
	v_cndmask_b32_e32 v99, 0, v99, vcc
	v_cmp_nlt_f32_e32 vcc, 0x42b17218, v98
	s_nop 1
	v_cndmask_b32_e32 v99, v192, v99, vcc
	v_mul_f32_e32 v77, v99, v77
	v_mul_f32_e64 v98, |v216|, v245
	v_mul_f32_e32 v99, 0x3fb8aa3b, v98
	v_fma_f32 v100, v98, s99, -v99
	v_rndne_f32_e32 v101, v99
	v_fmac_f32_e32 v100, 0x32a5705f, v98
	v_sub_f32_e32 v99, v99, v101
	v_add_f32_e32 v99, v99, v100
	v_exp_f32_e32 v99, v99
	v_cvt_i32_f32_e32 v100, v101
	v_cmp_ngt_f32_e32 vcc, 0xc2ce8ed0, v98
	v_ldexp_f32 v99, v99, v100
	s_nop 0
	v_cndmask_b32_e32 v99, 0, v99, vcc
	v_cmp_nlt_f32_e32 vcc, 0x42b17218, v98
	s_nop 1
	v_cndmask_b32_e32 v99, v192, v99, vcc
	v_mul_f32_e32 v78, v99, v78
	v_mul_f32_e64 v98, |v216|, v246
	v_mul_f32_e32 v99, 0x3fb8aa3b, v98
	v_fma_f32 v100, v98, s99, -v99
	v_rndne_f32_e32 v101, v99
	v_fmac_f32_e32 v100, 0x32a5705f, v98
	v_sub_f32_e32 v99, v99, v101
	v_add_f32_e32 v99, v99, v100
	v_exp_f32_e32 v99, v99
	v_cvt_i32_f32_e32 v100, v101
	v_cmp_ngt_f32_e32 vcc, 0xc2ce8ed0, v98
	v_ldexp_f32 v99, v99, v100
	s_nop 0
	v_cndmask_b32_e32 v99, 0, v99, vcc
	v_cmp_nlt_f32_e32 vcc, 0x42b17218, v98
	s_nop 1
	v_cndmask_b32_e32 v99, v192, v99, vcc
	v_mul_f32_e32 v79, v99, v79
	v_mul_f32_e64 v98, |v216|, v247
	v_mul_f32_e32 v99, 0x3fb8aa3b, v98
	v_fma_f32 v100, v98, s99, -v99
	v_rndne_f32_e32 v101, v99
	v_fmac_f32_e32 v100, 0x32a5705f, v98
	v_sub_f32_e32 v99, v99, v101
	v_add_f32_e32 v99, v99, v100
	v_exp_f32_e32 v99, v99
	v_cvt_i32_f32_e32 v100, v101
	v_cmp_ngt_f32_e32 vcc, 0xc2ce8ed0, v98
	v_ldexp_f32 v99, v99, v100
	s_nop 0
	v_cndmask_b32_e32 v99, 0, v99, vcc
	v_cmp_nlt_f32_e32 vcc, 0x42b17218, v98
	s_nop 1
	v_cndmask_b32_e32 v99, v192, v99, vcc
	v_mul_f32_e32 v80, v99, v80
	v_mul_f32_e64 v98, |v216|, v248
	v_mul_f32_e32 v99, 0x3fb8aa3b, v98
	v_fma_f32 v100, v98, s99, -v99
	v_rndne_f32_e32 v101, v99
	v_fmac_f32_e32 v100, 0x32a5705f, v98
	v_sub_f32_e32 v99, v99, v101
	v_add_f32_e32 v99, v99, v100
	v_exp_f32_e32 v99, v99
	v_cvt_i32_f32_e32 v100, v101
	v_cmp_ngt_f32_e32 vcc, 0xc2ce8ed0, v98
	v_ldexp_f32 v99, v99, v100
	s_nop 0
	v_cndmask_b32_e32 v99, 0, v99, vcc
	v_cmp_nlt_f32_e32 vcc, 0x42b17218, v98
	s_nop 1
	v_cndmask_b32_e32 v99, v192, v99, vcc
	v_mul_f32_e32 v81, v99, v81
	v_mul_f32_e64 v98, |v217|, v233
	v_mul_f32_e32 v99, 0x3fb8aa3b, v98
	v_fma_f32 v100, v98, s99, -v99
	v_rndne_f32_e32 v101, v99
	v_fmac_f32_e32 v100, 0x32a5705f, v98
	v_sub_f32_e32 v99, v99, v101
	v_add_f32_e32 v99, v99, v100
	v_exp_f32_e32 v99, v99
	v_cvt_i32_f32_e32 v100, v101
	v_cmp_ngt_f32_e32 vcc, 0xc2ce8ed0, v98
	v_ldexp_f32 v99, v99, v100
	s_nop 0
	v_cndmask_b32_e32 v99, 0, v99, vcc
	v_cmp_nlt_f32_e32 vcc, 0x42b17218, v98
	s_nop 1
	v_cndmask_b32_e32 v99, v192, v99, vcc
	v_mul_f32_e32 v82, v99, v82
	v_mul_f32_e64 v98, |v217|, v234
	v_mul_f32_e32 v99, 0x3fb8aa3b, v98
	v_fma_f32 v100, v98, s99, -v99
	v_rndne_f32_e32 v101, v99
	v_fmac_f32_e32 v100, 0x32a5705f, v98
	v_sub_f32_e32 v99, v99, v101
	v_add_f32_e32 v99, v99, v100
	v_exp_f32_e32 v99, v99
	v_cvt_i32_f32_e32 v100, v101
	v_cmp_ngt_f32_e32 vcc, 0xc2ce8ed0, v98
	v_ldexp_f32 v99, v99, v100
	s_nop 0
	v_cndmask_b32_e32 v99, 0, v99, vcc
	v_cmp_nlt_f32_e32 vcc, 0x42b17218, v98
	s_nop 1
	v_cndmask_b32_e32 v99, v192, v99, vcc
	v_mul_f32_e32 v83, v99, v83
	v_mul_f32_e64 v98, |v217|, v235
	v_mul_f32_e32 v99, 0x3fb8aa3b, v98
	v_fma_f32 v100, v98, s99, -v99
	v_rndne_f32_e32 v101, v99
	v_fmac_f32_e32 v100, 0x32a5705f, v98
	v_sub_f32_e32 v99, v99, v101
	v_add_f32_e32 v99, v99, v100
	v_exp_f32_e32 v99, v99
	v_cvt_i32_f32_e32 v100, v101
	v_cmp_ngt_f32_e32 vcc, 0xc2ce8ed0, v98
	v_ldexp_f32 v99, v99, v100
	s_nop 0
	v_cndmask_b32_e32 v99, 0, v99, vcc
	v_cmp_nlt_f32_e32 vcc, 0x42b17218, v98
	s_nop 1
	v_cndmask_b32_e32 v99, v192, v99, vcc
	v_mul_f32_e32 v84, v99, v84
	v_mul_f32_e64 v98, |v217|, v236
	v_mul_f32_e32 v99, 0x3fb8aa3b, v98
	v_fma_f32 v100, v98, s99, -v99
	v_rndne_f32_e32 v101, v99
	v_fmac_f32_e32 v100, 0x32a5705f, v98
	v_sub_f32_e32 v99, v99, v101
	v_add_f32_e32 v99, v99, v100
	v_exp_f32_e32 v99, v99
	v_cvt_i32_f32_e32 v100, v101
	v_cmp_ngt_f32_e32 vcc, 0xc2ce8ed0, v98
	v_ldexp_f32 v99, v99, v100
	s_nop 0
	v_cndmask_b32_e32 v99, 0, v99, vcc
	v_cmp_nlt_f32_e32 vcc, 0x42b17218, v98
	s_nop 1
	v_cndmask_b32_e32 v99, v192, v99, vcc
	v_mul_f32_e32 v85, v99, v85
	v_mul_f32_e64 v98, |v217|, v237
	v_mul_f32_e32 v99, 0x3fb8aa3b, v98
	v_fma_f32 v100, v98, s99, -v99
	v_rndne_f32_e32 v101, v99
	v_fmac_f32_e32 v100, 0x32a5705f, v98
	v_sub_f32_e32 v99, v99, v101
	v_add_f32_e32 v99, v99, v100
	v_exp_f32_e32 v99, v99
	v_cvt_i32_f32_e32 v100, v101
	v_cmp_ngt_f32_e32 vcc, 0xc2ce8ed0, v98
	v_ldexp_f32 v99, v99, v100
	s_nop 0
	v_cndmask_b32_e32 v99, 0, v99, vcc
	v_cmp_nlt_f32_e32 vcc, 0x42b17218, v98
	s_nop 1
	v_cndmask_b32_e32 v99, v192, v99, vcc
	v_mul_f32_e32 v86, v99, v86
	v_mul_f32_e64 v98, |v217|, v238
	v_mul_f32_e32 v99, 0x3fb8aa3b, v98
	v_fma_f32 v100, v98, s99, -v99
	v_rndne_f32_e32 v101, v99
	v_fmac_f32_e32 v100, 0x32a5705f, v98
	v_sub_f32_e32 v99, v99, v101
	v_add_f32_e32 v99, v99, v100
	v_exp_f32_e32 v99, v99
	v_cvt_i32_f32_e32 v100, v101
	v_cmp_ngt_f32_e32 vcc, 0xc2ce8ed0, v98
	v_ldexp_f32 v99, v99, v100
	s_nop 0
	v_cndmask_b32_e32 v99, 0, v99, vcc
	v_cmp_nlt_f32_e32 vcc, 0x42b17218, v98
	s_nop 1
	v_cndmask_b32_e32 v99, v192, v99, vcc
	v_mul_f32_e32 v87, v99, v87
	v_mul_f32_e64 v98, |v217|, v239
	v_mul_f32_e32 v99, 0x3fb8aa3b, v98
	v_fma_f32 v100, v98, s99, -v99
	v_rndne_f32_e32 v101, v99
	v_fmac_f32_e32 v100, 0x32a5705f, v98
	v_sub_f32_e32 v99, v99, v101
	v_add_f32_e32 v99, v99, v100
	v_exp_f32_e32 v99, v99
	v_cvt_i32_f32_e32 v100, v101
	v_cmp_ngt_f32_e32 vcc, 0xc2ce8ed0, v98
	v_ldexp_f32 v99, v99, v100
	s_nop 0
	v_cndmask_b32_e32 v99, 0, v99, vcc
	v_cmp_nlt_f32_e32 vcc, 0x42b17218, v98
	s_nop 1
	v_cndmask_b32_e32 v99, v192, v99, vcc
	v_mul_f32_e32 v88, v99, v88
	v_mul_f32_e64 v98, |v217|, v240
	v_mul_f32_e32 v99, 0x3fb8aa3b, v98
	v_fma_f32 v100, v98, s99, -v99
	v_rndne_f32_e32 v101, v99
	v_fmac_f32_e32 v100, 0x32a5705f, v98
	v_sub_f32_e32 v99, v99, v101
	v_add_f32_e32 v99, v99, v100
	v_exp_f32_e32 v99, v99
	v_cvt_i32_f32_e32 v100, v101
	v_cmp_ngt_f32_e32 vcc, 0xc2ce8ed0, v98
	v_ldexp_f32 v99, v99, v100
	s_nop 0
	v_cndmask_b32_e32 v99, 0, v99, vcc
	v_cmp_nlt_f32_e32 vcc, 0x42b17218, v98
	s_nop 1
	v_cndmask_b32_e32 v99, v192, v99, vcc
	v_mul_f32_e32 v89, v99, v89
	v_mul_f32_e64 v98, |v217|, v241
	v_mul_f32_e32 v99, 0x3fb8aa3b, v98
	v_fma_f32 v100, v98, s99, -v99
	v_rndne_f32_e32 v101, v99
	v_fmac_f32_e32 v100, 0x32a5705f, v98
	v_sub_f32_e32 v99, v99, v101
	v_add_f32_e32 v99, v99, v100
	v_exp_f32_e32 v99, v99
	v_cvt_i32_f32_e32 v100, v101
	v_cmp_ngt_f32_e32 vcc, 0xc2ce8ed0, v98
	v_ldexp_f32 v99, v99, v100
	s_nop 0
	v_cndmask_b32_e32 v99, 0, v99, vcc
	v_cmp_nlt_f32_e32 vcc, 0x42b17218, v98
	s_nop 1
	v_cndmask_b32_e32 v99, v192, v99, vcc
	v_mul_f32_e32 v90, v99, v90
	v_mul_f32_e64 v98, |v217|, v242
	v_mul_f32_e32 v99, 0x3fb8aa3b, v98
	v_fma_f32 v100, v98, s99, -v99
	v_rndne_f32_e32 v101, v99
	v_fmac_f32_e32 v100, 0x32a5705f, v98
	v_sub_f32_e32 v99, v99, v101
	v_add_f32_e32 v99, v99, v100
	v_exp_f32_e32 v99, v99
	v_cvt_i32_f32_e32 v100, v101
	v_cmp_ngt_f32_e32 vcc, 0xc2ce8ed0, v98
	v_ldexp_f32 v99, v99, v100
	s_nop 0
	v_cndmask_b32_e32 v99, 0, v99, vcc
	v_cmp_nlt_f32_e32 vcc, 0x42b17218, v98
	s_nop 1
	v_cndmask_b32_e32 v99, v192, v99, vcc
	v_mul_f32_e32 v91, v99, v91
	v_mul_f32_e64 v98, |v217|, v243
	v_mul_f32_e32 v99, 0x3fb8aa3b, v98
	v_fma_f32 v100, v98, s99, -v99
	v_rndne_f32_e32 v101, v99
	v_fmac_f32_e32 v100, 0x32a5705f, v98
	v_sub_f32_e32 v99, v99, v101
	v_add_f32_e32 v99, v99, v100
	v_exp_f32_e32 v99, v99
	v_cvt_i32_f32_e32 v100, v101
	v_cmp_ngt_f32_e32 vcc, 0xc2ce8ed0, v98
	v_ldexp_f32 v99, v99, v100
	s_nop 0
	v_cndmask_b32_e32 v99, 0, v99, vcc
	v_cmp_nlt_f32_e32 vcc, 0x42b17218, v98
	s_nop 1
	v_cndmask_b32_e32 v99, v192, v99, vcc
	v_mul_f32_e32 v92, v99, v92
	v_mul_f32_e64 v98, |v217|, v244
	v_mul_f32_e32 v99, 0x3fb8aa3b, v98
	v_fma_f32 v100, v98, s99, -v99
	v_rndne_f32_e32 v101, v99
	v_fmac_f32_e32 v100, 0x32a5705f, v98
	v_sub_f32_e32 v99, v99, v101
	v_add_f32_e32 v99, v99, v100
	v_exp_f32_e32 v99, v99
	v_cvt_i32_f32_e32 v100, v101
	v_cmp_ngt_f32_e32 vcc, 0xc2ce8ed0, v98
	v_ldexp_f32 v99, v99, v100
	s_nop 0
	v_cndmask_b32_e32 v99, 0, v99, vcc
	v_cmp_nlt_f32_e32 vcc, 0x42b17218, v98
	s_nop 1
	v_cndmask_b32_e32 v99, v192, v99, vcc
	v_mul_f32_e32 v93, v99, v93
	v_mul_f32_e64 v98, |v217|, v245
	v_mul_f32_e32 v99, 0x3fb8aa3b, v98
	v_fma_f32 v100, v98, s99, -v99
	v_rndne_f32_e32 v101, v99
	v_fmac_f32_e32 v100, 0x32a5705f, v98
	v_sub_f32_e32 v99, v99, v101
	v_add_f32_e32 v99, v99, v100
	v_exp_f32_e32 v99, v99
	v_cvt_i32_f32_e32 v100, v101
	v_cmp_ngt_f32_e32 vcc, 0xc2ce8ed0, v98
	v_ldexp_f32 v99, v99, v100
	s_nop 0
	v_cndmask_b32_e32 v99, 0, v99, vcc
	v_cmp_nlt_f32_e32 vcc, 0x42b17218, v98
	s_nop 1
	v_cndmask_b32_e32 v99, v192, v99, vcc
	v_mul_f32_e32 v94, v99, v94
	v_mul_f32_e64 v98, |v217|, v246
	v_mul_f32_e32 v99, 0x3fb8aa3b, v98
	v_fma_f32 v100, v98, s99, -v99
	v_rndne_f32_e32 v101, v99
	v_fmac_f32_e32 v100, 0x32a5705f, v98
	v_sub_f32_e32 v99, v99, v101
	v_add_f32_e32 v99, v99, v100
	v_exp_f32_e32 v99, v99
	v_cvt_i32_f32_e32 v100, v101
	v_cmp_ngt_f32_e32 vcc, 0xc2ce8ed0, v98
	v_ldexp_f32 v99, v99, v100
	s_nop 0
	v_cndmask_b32_e32 v99, 0, v99, vcc
	v_cmp_nlt_f32_e32 vcc, 0x42b17218, v98
	s_nop 1
	v_cndmask_b32_e32 v99, v192, v99, vcc
	v_mul_f32_e32 v95, v99, v95
	v_mul_f32_e64 v98, |v217|, v247
	v_mul_f32_e32 v99, 0x3fb8aa3b, v98
	v_fma_f32 v100, v98, s99, -v99
	v_rndne_f32_e32 v101, v99
	v_fmac_f32_e32 v100, 0x32a5705f, v98
	v_sub_f32_e32 v99, v99, v101
	v_add_f32_e32 v99, v99, v100
	v_exp_f32_e32 v99, v99
	v_cvt_i32_f32_e32 v100, v101
	v_cmp_ngt_f32_e32 vcc, 0xc2ce8ed0, v98
	v_ldexp_f32 v99, v99, v100
	s_nop 0
	v_cndmask_b32_e32 v99, 0, v99, vcc
	v_cmp_nlt_f32_e32 vcc, 0x42b17218, v98
	s_nop 1
	v_cndmask_b32_e32 v99, v192, v99, vcc
	v_mul_f32_e32 v96, v99, v96
	v_mul_f32_e64 v98, |v217|, v248
	v_mul_f32_e32 v99, 0x3fb8aa3b, v98
	v_fma_f32 v100, v98, s99, -v99
	v_rndne_f32_e32 v101, v99
	v_fmac_f32_e32 v100, 0x32a5705f, v98
	v_sub_f32_e32 v99, v99, v101
	v_add_f32_e32 v99, v99, v100
	v_exp_f32_e32 v99, v99
	v_cvt_i32_f32_e32 v100, v101
	v_cmp_ngt_f32_e32 vcc, 0xc2ce8ed0, v98
	v_ldexp_f32 v99, v99, v100
	s_nop 0
	v_cndmask_b32_e32 v99, 0, v99, vcc
	v_cmp_nlt_f32_e32 vcc, 0x42b17218, v98
	s_nop 1
	v_cndmask_b32_e32 v99, v192, v99, vcc
	v_mul_f32_e32 v97, v99, v97
	v_and_b32_e32 v81, v232, v81
	v_and_b32_e32 v97, v232, v97
	s_lshl_b32 s0, s3, 6
	s_cmp_lg_u32 s96, 0
	s_cbranch_scc1 .Lff_dir1
	s_sub_u32 s0, s74, s0
	s_subb_u32 s1, s75, 0
	v_cvt_pk_bf16_f32 v102, v69, v68
	v_cvt_pk_bf16_f32 v103, v67, v66
	global_store_dwordx2 v218, v[102:103], s[0:1]
	v_cvt_pk_bf16_f32 v104, v73, v72
	v_cvt_pk_bf16_f32 v105, v71, v70
	global_store_dwordx2 v218, v[104:105], s[0:1] offset:-16
	v_cvt_pk_bf16_f32 v102, v77, v76
	v_cvt_pk_bf16_f32 v103, v75, v74
	global_store_dwordx2 v218, v[102:103], s[0:1] offset:-32
	v_cvt_pk_bf16_f32 v104, v81, v80
	v_cvt_pk_bf16_f32 v105, v79, v78
	global_store_dwordx2 v218, v[104:105], s[0:1] offset:-48
	v_cvt_pk_bf16_f32 v102, v85, v84
	v_cvt_pk_bf16_f32 v103, v83, v82
	global_store_dwordx2 v219, v[102:103], s[0:1]
	v_cvt_pk_bf16_f32 v104, v89, v88
	v_cvt_pk_bf16_f32 v105, v87, v86
	global_store_dwordx2 v219, v[104:105], s[0:1] offset:-16
	v_cvt_pk_bf16_f32 v102, v93, v92
	v_cvt_pk_bf16_f32 v103, v91, v90
	global_store_dwordx2 v219, v[102:103], s[0:1] offset:-32
	v_cvt_pk_bf16_f32 v104, v97, v96
	v_cvt_pk_bf16_f32 v105, v95, v94
	global_store_dwordx2 v219, v[104:105], s[0:1] offset:-48
	s_branch .Lff_next
.Lff_dir1:
	s_add_u32 s0, s74, s0
	s_addc_u32 s1, s75, 0
	v_cvt_pk_bf16_f32 v102, v66, v67
	v_cvt_pk_bf16_f32 v103, v68, v69
	global_store_dwordx2 v218, v[102:103], s[0:1]
	v_cvt_pk_bf16_f32 v104, v70, v71
	v_cvt_pk_bf16_f32 v105, v72, v73
	global_store_dwordx2 v218, v[104:105], s[0:1] offset:16
	v_cvt_pk_bf16_f32 v102, v74, v75
	v_cvt_pk_bf16_f32 v103, v76, v77
	global_store_dwordx2 v218, v[102:103], s[0:1] offset:32
	v_cvt_pk_bf16_f32 v104, v78, v79
	v_cvt_pk_bf16_f32 v105, v80, v81
	global_store_dwordx2 v218, v[104:105], s[0:1] offset:48
	v_cvt_pk_bf16_f32 v102, v82, v83
	v_cvt_pk_bf16_f32 v103, v84, v85
	global_store_dwordx2 v219, v[102:103], s[0:1]
	v_cvt_pk_bf16_f32 v104, v86, v87
	v_cvt_pk_bf16_f32 v105, v88, v89
	global_store_dwordx2 v219, v[104:105], s[0:1] offset:16
	v_cvt_pk_bf16_f32 v102, v90, v91
	v_cvt_pk_bf16_f32 v103, v92, v93
	global_store_dwordx2 v219, v[102:103], s[0:1] offset:32
	v_cvt_pk_bf16_f32 v104, v94, v95
	v_cvt_pk_bf16_f32 v105, v96, v97
	global_store_dwordx2 v219, v[104:105], s[0:1] offset:48
.Lff_next:
	s_add_i32 s3, s3, 1
	s_cmp_lt_u32 s3, s101
	s_cbranch_scc1 .Lff_pt
	s_cmpk_ge_i32 s4, 0x200
	s_cbranch_scc1 .Lff_done
	s_cmpk_ge_u32 s94, 0x80
	s_cbranch_scc1 .Lff_done
	s_lshr_b32 s4, s94, 1
	s_addk_i32 s4, 0x200
	s_and_b32 s100, s94, 1
	s_add_i32 s101, s100, 1
	s_branch .Lff_item
.Lff_done:
	s_branch .LBB0_555
.LBB0_539:
	s_or_b64 exec, exec, s[8:9]
	v_readlane_b32 s0, v254, 57
	s_cmp_lg_u32 s0, 1
	s_cbranch_scc1 .LBB0_555
	v_readlane_b32 s1, v254, 41
	s_nop 3
	s_cmpk_eq_i32 s1, 0x200
	s_cbranch_scc1 .Lfilt_fast
	v_mov_b32_e32 v0, v176
	s_mov_b32 s4, s94
	s_cmpk_gt_i32 s4, 0x23f
	s_cbranch_scc1 .LBB0_555
	v_readlane_b32 s8, v252, 0
	s_movk_i32 s0, 0x400
	v_ashrrev_i32_e32 v1, 31, v0
	v_readlane_b32 s20, v252, 12
	v_readlane_b32 s21, v252, 13
	v_cmp_gt_i32_e64 s[0:1], s0, v0
	v_add_u32_e32 v10, 0xffffff00, v0
	v_lshlrev_b32_e32 v11, 4, v0
	v_lshl_add_u64 v[2:3], v[0:1], 4, s[20:21]
	v_readlane_b32 s9, v252, 1
	v_readlane_b32 s10, v252, 2
	v_readlane_b32 s11, v252, 3
	v_readlane_b32 s12, v252, 4
	v_readlane_b32 s13, v252, 5
	v_readlane_b32 s14, v252, 6
	v_readlane_b32 s15, v252, 7
	v_readlane_b32 s16, v252, 8
	v_readlane_b32 s17, v252, 9
	v_readlane_b32 s18, v252, 10
	v_readlane_b32 s19, v252, 11
	v_readlane_b32 s22, v252, 14
	v_readlane_b32 s23, v252, 15
	s_branch .LBB0_543
